# U: EpiGU rs row scales loaded at tile start into registers the K loop does not touch; epilogue-head vmcnt(0) removed
# speedup vs baseline: 1.0078x; 1.0078x over previous
; template <class Epi, class Sched, bool ALIGN_EPI = false, bool SP2 = false>
; __device__ __forceinline__ void gemm_phase(PG8_LAS unsigned char* lds, const Gemm g, const Sched& S, const Epi& E) {
;     ...
; #pragma unroll
;         for (int a = 0; a < 2; ++a)
; #pragma unroll
;             for (int b = 0; b < 2; ++b)
; #pragma unroll
;                 for (int m = 0; m < 4; ++m)
; #pragma unroll
;                     for (int n = 0; n < 2; ++n) acc[a][b][m][n] = (f32x4){0.f, 0.f, 0.f, 0.f};
;     __device__ __forceinline__ void operator()(const f32x4 (&acc)[2][2][4][2], const Unit& u, int wr, int wc, int fr, int fq) const {
;         const int row0 = u.pm * 256 + wr * 64 + fr, col0 = u.pn * 128 + wc * 32 + fq * 8;
;         float sv[2][4];
; #pragma unroll
;         for (int ai = 0; ai < 2; ++ai)
; #pragma unroll
;             for (int m = 0; m < 4; ++m) sv[ai][m] = rs[row0 + ai * 128 + m * 16];
.LBB0_724:
	s_ashr_i32 s11, s10, 31
	s_lshl_b64 s[12:13], s[10:11], 20
	v_readlane_b32 s14, v251, 8
	v_readlane_b32 s15, v251, 9
	s_add_u32 s12, s14, s12
	s_addc_u32 s13, s15, s13
	s_and_b64 s[14:15], s[6:7], exec
	s_cselect_b32 s11, s13, s19
	s_cselect_b32 s33, s12, s18
	s_ashr_i32 s9, s8, 31
	s_lshl_b64 s[14:15], s[8:9], 20
	s_add_u32 s14, s26, s14
	s_addc_u32 s15, s27, s15
	s_and_b64 s[22:23], s[6:7], exec
	s_cselect_b32 s9, s15, s21
	s_cselect_b32 s38, s14, s20
	s_add_u32 s18, s18, 0x80080
	s_addc_u32 s19, s19, 0
	s_add_u32 s39, s20, 0x100
	v_mov_b32_e32 v0, 0
	s_addc_u32 s40, s21, 0
	s_mov_b32 s41, -2
	v_mov_b32_e32 v1, v0
	v_mov_b32_e32 v2, v0
	v_mov_b32_e32 v3, v0
	v_mov_b32_e32 v8, v0
	v_mov_b32_e32 v9, v0
	v_mov_b32_e32 v10, v0
	v_mov_b32_e32 v11, v0
	v_mov_b32_e32 v16, v0
	v_mov_b32_e32 v17, v0
	v_mov_b32_e32 v18, v0
	v_mov_b32_e32 v19, v0
	v_mov_b32_e32 v24, v0
	v_mov_b32_e32 v25, v0
	v_mov_b32_e32 v26, v0
	v_mov_b32_e32 v27, v0
	v_mov_b32_e32 v32, v0
	v_mov_b32_e32 v33, v0
	v_mov_b32_e32 v34, v0
	v_mov_b32_e32 v35, v0
	v_mov_b32_e32 v40, v0
	v_mov_b32_e32 v41, v0
	v_mov_b32_e32 v42, v0
	v_mov_b32_e32 v43, v0
	v_mov_b32_e32 v48, v0
	v_mov_b32_e32 v49, v0
	v_mov_b32_e32 v50, v0
	v_mov_b32_e32 v51, v0
	v_mov_b32_e32 v56, v0
	v_mov_b32_e32 v57, v0
	v_mov_b32_e32 v58, v0
	v_mov_b32_e32 v59, v0
	v_mov_b32_e32 v4, v0
	v_mov_b32_e32 v5, v0
	v_mov_b32_e32 v6, v0
	v_mov_b32_e32 v7, v0
	v_mov_b32_e32 v12, v0
	v_mov_b32_e32 v13, v0
	v_mov_b32_e32 v14, v0
	v_mov_b32_e32 v15, v0
	v_mov_b32_e32 v20, v0
	v_mov_b32_e32 v21, v0
	v_mov_b32_e32 v22, v0
	v_mov_b32_e32 v23, v0
	v_mov_b32_e32 v28, v0
	v_mov_b32_e32 v29, v0
	v_mov_b32_e32 v30, v0
	v_mov_b32_e32 v31, v0
	v_mov_b32_e32 v36, v0
	v_mov_b32_e32 v37, v0
	v_mov_b32_e32 v38, v0
	v_mov_b32_e32 v39, v0
	v_mov_b32_e32 v44, v0
	v_mov_b32_e32 v45, v0
	v_mov_b32_e32 v46, v0
	v_mov_b32_e32 v47, v0
	v_mov_b32_e32 v52, v0
	v_mov_b32_e32 v53, v0
	v_mov_b32_e32 v54, v0
	v_mov_b32_e32 v55, v0
	v_mov_b32_e32 v60, v0
	v_mov_b32_e32 v61, v0
	v_mov_b32_e32 v62, v0
	v_mov_b32_e32 v63, v0
	v_mov_b32_e32 v64, v0
	v_mov_b32_e32 v65, v0
	v_mov_b32_e32 v66, v0
	v_mov_b32_e32 v67, v0
	v_mov_b32_e32 v72, v0
	v_mov_b32_e32 v73, v0
	v_mov_b32_e32 v74, v0
	v_mov_b32_e32 v75, v0
	s_waitcnt vmcnt(0)
	v_mov_b32_e32 v80, v0
	v_mov_b32_e32 v81, v0
	v_mov_b32_e32 v82, v0
	v_mov_b32_e32 v83, v0
	v_mov_b32_e32 v88, v0
	v_mov_b32_e32 v89, v0
	v_mov_b32_e32 v90, v0
	v_mov_b32_e32 v91, v0
	v_mov_b32_e32 v96, v0
	v_mov_b32_e32 v97, v0
	v_mov_b32_e32 v98, v0
	v_mov_b32_e32 v99, v0
	v_mov_b32_e32 v104, v0
	v_mov_b32_e32 v105, v0
	v_mov_b32_e32 v106, v0
	v_mov_b32_e32 v107, v0
	v_mov_b32_e32 v116, v0
	v_mov_b32_e32 v117, v0
	v_mov_b32_e32 v118, v0
	v_mov_b32_e32 v119, v0
	v_mov_b32_e32 v120, v0
	v_mov_b32_e32 v121, v0
	v_mov_b32_e32 v122, v0
	v_mov_b32_e32 v123, v0
	v_mov_b32_e32 v68, v0
	v_mov_b32_e32 v69, v0
	v_mov_b32_e32 v70, v0
	v_mov_b32_e32 v71, v0
	v_mov_b32_e32 v76, v0
	v_mov_b32_e32 v77, v0
	v_mov_b32_e32 v78, v0
	v_mov_b32_e32 v79, v0
	v_mov_b32_e32 v84, v0
	v_mov_b32_e32 v85, v0
	v_mov_b32_e32 v86, v0
	v_mov_b32_e32 v87, v0
	v_mov_b32_e32 v92, v0
	v_mov_b32_e32 v93, v0
	v_mov_b32_e32 v94, v0
	v_mov_b32_e32 v95, v0
	v_mov_b32_e32 v100, v0
	v_mov_b32_e32 v101, v0
	v_mov_b32_e32 v102, v0
	v_mov_b32_e32 v103, v0
	v_mov_b32_e32 v108, v0
	v_mov_b32_e32 v109, v0
	v_mov_b32_e32 v110, v0
	v_mov_b32_e32 v111, v0
	v_mov_b32_e32 v112, v0
	v_mov_b32_e32 v113, v0
	v_mov_b32_e32 v114, v0
	v_mov_b32_e32 v115, v0
	v_mov_b32_e32 v124, v0
	v_mov_b32_e32 v125, v0
	v_mov_b32_e32 v126, v0
	v_mov_b32_e32 v127, v0
	v_readlane_b32 s100, v251, 10
	v_readlane_b32 s101, v251, 11
	v_lshl_add_u32 v245, s16, 8, v147
	v_lshlrev_b32_e32 v245, 2, v245
	s_nop 3
	global_load_dword v142, v245, s[100:101]
	global_load_dword v190, v245, s[100:101] offset:64
	global_load_dword v244, v245, s[100:101] offset:128
	global_load_dword v186, v245, s[100:101] offset:192
	global_load_dword v152, v245, s[100:101] offset:512
	global_load_dword v150, v245, s[100:101] offset:576
	global_load_dword v148, v245, s[100:101] offset:640
	global_load_dword v188, v245, s[100:101] offset:704
	s_mov_b64 s[50:51], 0x80

; __device__ __forceinline__ unsigned cvt_pk_bf16(float lo, float hi) { unsigned r; asm volatile("v_cvt_pk_bf16_f32 %0, %1, %2" : "=v"(r) : "v"(lo), "v"(hi)); return r; }
; __device__ __forceinline__ float sigmoidf_(float x) { return __builtin_amdgcn_rcpf(1.0f + __expf(-x)); }
;     __device__ __forceinline__ void operator()(const f32x4 (&acc)[2][2][4][2], const Unit& u, int wr, int wc, int fr, int fq) const {
;         const int row0 = u.pm * 256 + wr * 64 + fr, col0 = u.pn * 128 + wc * 32 + fq * 8;
;         float sv[2][4];
; #pragma unroll
;         for (int ai = 0; ai < 2; ++ai)
; #pragma unroll
;             for (int m = 0; m < 4; ++m) sv[ai][m] = rs[row0 + ai * 128 + m * 16];
; #pragma unroll
;         for (int ai = 0; ai < 2; ++ai)
; #pragma unroll
;             for (int m = 0; m < 4; ++m) {
;                 const int row = row0 + ai * 128 + m * 16; const float s = sv[ai][m];
;                 float o[8];
; #pragma unroll
;                 for (int n = 0; n < 2; ++n)
; #pragma unroll
;                     for (int j = 0; j < 4; ++j) { const float g = acc[ai][0][m][n][j] * s, up = acc[ai][1][m][n][j] * s; o[n * 4 + j] = g * sigmoidf_(g) * up; }
;                 u32x4 w; w.x = cvt_pk_bf16(o[0], o[1]); w.y = cvt_pk_bf16(o[2], o[3]); w.z = cvt_pk_bf16(o[4], o[5]); w.w = cvt_pk_bf16(o[6], o[7]);
;                 *(u32x4*)(ACT + (size_t)row * FF + col0) = w;
.LBB0_728:
	v_lshl_add_u32 v166, s16, 8, v147
	v_readlane_b32 s18, v251, 10
	v_ashrrev_i32_e32 v167, 31, v166
	v_readlane_b32 s19, v251, 11
	v_or_b32_e32 v162, 16, v166
	v_ashrrev_i32_e32 v163, 31, v162
	v_lshl_add_u64 v[138:139], v[166:167], 2, s[18:19]
	v_lshl_add_u64 v[140:141], v[162:163], 2, s[18:19]
	v_mov_b32_e32 v139, v124
	v_mov_b32_e32 v124, v121
	v_mov_b32_e32 v138, v120
	v_or_b32_e32 v158, 32, v166
	v_ashrrev_i32_e32 v159, 31, v158
	v_or_b32_e32 v154, 48, v166
	v_lshl_add_u64 v[140:141], v[158:159], 2, s[18:19]
	v_ashrrev_i32_e32 v155, 31, v154
	v_lshl_or_b32 v168, s17, 7, v151
	v_readlane_b32 s16, v251, 14
	v_lshl_add_u64 v[140:141], v[154:155], 2, s[18:19]
	v_readlane_b32 s17, v251, 15
	v_ashrrev_i32_e32 v169, 31, v168
	s_movk_i32 s3, 0x2b00
	v_add_u32_e32 v161, 0x80, v166
	v_add_u32_e32 v157, 0xa0, v166
	v_add_u32_e32 v159, 0x90, v166
	v_add_u32_e32 v155, 0xb0, v166
	s_andn2_b64 vcc, exec, s[6:7]
	v_pk_mul_f32 v[124:125], v[124:125], v[142:143] op_sel_hi:[1,0]
	s_nop 0
	v_mul_f32_e32 v121, 0xbfb8aa3b, v125
	v_exp_f32_e32 v121, v121
	v_pk_mul_f32 v[138:139], v[138:139], v[142:143] op_sel_hi:[1,0]
	v_add_f32_e32 v121, 1.0, v121
	v_rcp_f32_e32 v121, v121
	v_mul_f32_e32 v120, 0xbfb8aa3b, v139
	v_exp_f32_e32 v120, v120
	v_mul_f32_e32 v121, v125, v121
	v_mul_f32_e32 v121, v124, v121
	v_mov_b32_e32 v124, v122
	v_mov_b32_e32 v125, v126
	v_pk_mul_f32 v[124:125], v[124:125], v[142:143] op_sel_hi:[1,0]
	v_mov_b32_e32 v126, v123
	v_mul_f32_e32 v122, 0xbfb8aa3b, v125
	v_exp_f32_e32 v122, v122
	v_add_f32_e32 v120, 1.0, v120
	v_rcp_f32_e32 v120, v120
	v_add_f32_e32 v122, 1.0, v122
	v_rcp_f32_e32 v122, v122
	v_mul_f32_e32 v120, v139, v120
	v_mul_f32_e32 v120, v138, v120
	v_mul_f32_e32 v122, v125, v122
	v_mul_f32_e32 v124, v124, v122
	v_pk_mul_f32 v[122:123], v[126:127], v[142:143] op_sel_hi:[1,0]
	s_nop 0
	v_mul_f32_e32 v125, 0xbfb8aa3b, v123
	v_exp_f32_e32 v125, v125
	s_nop 0
	v_add_f32_e32 v125, 1.0, v125
	v_rcp_f32_e32 v125, v125
	s_nop 0
	v_mul_f32_e32 v123, v123, v125
	v_mul_f32_e32 v125, v122, v123
	v_mov_b32_e32 v122, v116
	v_mov_b32_e32 v123, v112
	v_pk_mul_f32 v[122:123], v[122:123], v[142:143] op_sel_hi:[1,0]
	s_nop 0
	v_mul_f32_e32 v112, 0xbfb8aa3b, v123
	v_exp_f32_e32 v112, v112
	s_nop 0
	v_add_f32_e32 v112, 1.0, v112
	v_rcp_f32_e32 v112, v112
	s_nop 0
	v_mul_f32_e32 v112, v123, v112
	v_mul_f32_e32 v122, v122, v112
	v_mov_b32_e32 v112, v117
	v_pk_mul_f32 v[112:113], v[112:113], v[142:143] op_sel_hi:[1,0]
	s_nop 0
	v_mul_f32_e32 v116, 0xbfb8aa3b, v113
	v_exp_f32_e32 v116, v116
	s_nop 0
	v_add_f32_e32 v116, 1.0, v116
	v_rcp_f32_e32 v116, v116
	s_nop 0
	v_mul_f32_e32 v113, v113, v116
	v_mul_f32_e32 v123, v112, v113
	v_mov_b32_e32 v112, v118
	v_mov_b32_e32 v113, v114
	v_pk_mul_f32 v[112:113], v[112:113], v[142:143] op_sel_hi:[1,0]
	v_cvt_pk_bf16_f32 v116, v120, v121
	v_cvt_pk_bf16_f32 v117, v124, v125
	v_cvt_pk_bf16_f32 v118, v122, v123
	s_nop 0
	v_mul_f32_e32 v114, 0xbfb8aa3b, v113
	v_exp_f32_e32 v114, v114
	s_nop 0
	v_add_f32_e32 v114, 1.0, v114
	v_rcp_f32_e32 v114, v114
	s_nop 0
	v_mul_f32_e32 v113, v113, v114
	v_mov_b32_e32 v114, v119
	v_mul_f32_e32 v126, v112, v113
	v_pk_mul_f32 v[112:113], v[114:115], v[142:143] op_sel_hi:[1,0]
	s_nop 0
	v_mul_f32_e32 v114, 0xbfb8aa3b, v113
	v_exp_f32_e32 v114, v114
	s_nop 0
	v_add_f32_e32 v114, 1.0, v114
	v_rcp_f32_e32 v114, v114
	s_nop 0
	v_mul_f32_e32 v113, v113, v114
	v_mul_f32_e32 v112, v112, v113
	v_cvt_pk_bf16_f32 v119, v126, v112
	v_mov_b64_e32 v[112:113], s[16:17]
	v_mad_i64_i32 v[120:121], s[16:17], v166, s3, v[112:113]
	v_lshlrev_b64 v[114:115], 1, v[168:169]
	v_lshl_add_u64 v[120:121], v[120:121], 0, v[114:115]
	global_store_dwordx4 v[120:121], v[116:119], off
	s_nop 1
	v_mov_b32_e32 v116, v104
	v_mov_b32_e32 v117, v108
	v_pk_mul_f32 v[116:117], v[116:117], v[190:191] op_sel_hi:[1,0]
	v_mov_b32_e32 v108, v105
	v_mul_f32_e32 v104, 0xbfb8aa3b, v117
	v_exp_f32_e32 v104, v104
	s_nop 0
	v_add_f32_e32 v104, 1.0, v104
	v_rcp_f32_e32 v104, v104
	s_nop 0
	v_mul_f32_e32 v104, v117, v104
	v_mul_f32_e32 v116, v116, v104
	v_pk_mul_f32 v[104:105], v[108:109], v[190:191] op_sel_hi:[1,0]
	s_nop 0
	v_mul_f32_e32 v108, 0xbfb8aa3b, v105
	v_exp_f32_e32 v108, v108
	s_nop 0
	v_add_f32_e32 v108, 1.0, v108
	v_rcp_f32_e32 v108, v108
	s_nop 0
	v_mul_f32_e32 v105, v105, v108
	v_mul_f32_e32 v108, v104, v105
	v_mov_b32_e32 v104, v106
	v_mov_b32_e32 v105, v110
	v_pk_mul_f32 v[104:105], v[104:105], v[190:191] op_sel_hi:[1,0]
	v_mov_b32_e32 v110, v107
	v_mul_f32_e32 v106, 0xbfb8aa3b, v105
	v_exp_f32_e32 v106, v106
	s_nop 0
	v_add_f32_e32 v106, 1.0, v106
	v_rcp_f32_e32 v106, v106
	s_nop 0
	v_mul_f32_e32 v105, v105, v106
	v_mul_f32_e32 v106, v104, v105
	v_pk_mul_f32 v[104:105], v[110:111], v[190:191] op_sel_hi:[1,0]
	s_nop 0
	v_mul_f32_e32 v107, 0xbfb8aa3b, v105
	v_exp_f32_e32 v107, v107
	s_nop 0
	v_add_f32_e32 v107, 1.0, v107
	v_rcp_f32_e32 v107, v107
	s_nop 0
	v_mul_f32_e32 v105, v105, v107
	v_mul_f32_e32 v107, v104, v105
	v_mov_b32_e32 v104, v96
	v_mov_b32_e32 v105, v100
	v_pk_mul_f32 v[104:105], v[104:105], v[190:191] op_sel_hi:[1,0]
	v_mov_b32_e32 v100, v97
	v_mul_f32_e32 v96, 0xbfb8aa3b, v105
	v_exp_f32_e32 v96, v96
	s_nop 0
	v_add_f32_e32 v96, 1.0, v96
	v_rcp_f32_e32 v96, v96
	s_nop 0
	v_mul_f32_e32 v96, v105, v96
	v_mul_f32_e32 v104, v104, v96
	v_pk_mul_f32 v[96:97], v[100:101], v[190:191] op_sel_hi:[1,0]
	s_nop 0
	v_mul_f32_e32 v100, 0xbfb8aa3b, v97
	v_exp_f32_e32 v100, v100
	s_nop 0
	v_add_f32_e32 v100, 1.0, v100
	v_rcp_f32_e32 v100, v100
	s_nop 0
	v_mul_f32_e32 v97, v97, v100
	v_mul_f32_e32 v100, v96, v97
	v_mov_b32_e32 v96, v98
	v_mov_b32_e32 v97, v102
	v_pk_mul_f32 v[96:97], v[96:97], v[190:191] op_sel_hi:[1,0]
; __device__ __forceinline__ unsigned cvt_pk_bf16(float lo, float hi) { unsigned r; asm volatile("v_cvt_pk_bf16_f32 %0, %1, %2" : "=v"(r) : "v"(lo), "v"(hi)); return r; }
; __device__ __forceinline__ float sigmoidf_(float x) { return __builtin_amdgcn_rcpf(1.0f + __expf(-x)); }
;     __device__ __forceinline__ void operator()(const f32x4 (&acc)[2][2][4][2], const Unit& u, int wr, int wc, int fr, int fq) const {
;     ...
;         for (int ai = 0; ai < 2; ++ai)
; #pragma unroll
;             for (int m = 0; m < 4; ++m) {
;                 const int row = row0 + ai * 128 + m * 16; const float s = sv[ai][m];
;                 float o[8];
; #pragma unroll
;                 for (int n = 0; n < 2; ++n)
; #pragma unroll
;                     for (int j = 0; j < 4; ++j) { const float g = acc[ai][0][m][n][j] * s, up = acc[ai][1][m][n][j] * s; o[n * 4 + j] = g * sigmoidf_(g) * up; }
;                 u32x4 w; w.x = cvt_pk_bf16(o[0], o[1]); w.y = cvt_pk_bf16(o[2], o[3]); w.z = cvt_pk_bf16(o[4], o[5]); w.w = cvt_pk_bf16(o[6], o[7]);
;                 *(u32x4*)(ACT + (size_t)row * FF + col0) = w;
	v_mov_b32_e32 v102, v99
	v_mul_f32_e32 v98, 0xbfb8aa3b, v97
	v_exp_f32_e32 v98, v98
	s_nop 0
	v_add_f32_e32 v98, 1.0, v98
	v_rcp_f32_e32 v98, v98
	s_nop 0
	v_mul_f32_e32 v97, v97, v98
	v_mul_f32_e32 v101, v96, v97
	v_pk_mul_f32 v[96:97], v[102:103], v[190:191] op_sel_hi:[1,0]
	s_nop 0
	v_mul_f32_e32 v98, 0xbfb8aa3b, v97
	v_exp_f32_e32 v98, v98
	s_nop 0
	v_add_f32_e32 v98, 1.0, v98
	v_rcp_f32_e32 v98, v98
	s_nop 0
	v_mul_f32_e32 v97, v97, v98
	v_mul_f32_e32 v99, v96, v97
	v_cvt_pk_bf16_f32 v96, v116, v108
	v_cvt_pk_bf16_f32 v97, v106, v107
	v_cvt_pk_bf16_f32 v98, v104, v100
	v_cvt_pk_bf16_f32 v99, v101, v99
	v_mad_i64_i32 v[100:101], s[16:17], v162, s3, v[112:113]
	v_lshl_add_u64 v[100:101], v[100:101], 0, v[114:115]
	global_store_dwordx4 v[100:101], v[96:99], off
	s_nop 1
	v_mov_b32_e32 v96, v88
	v_mov_b32_e32 v97, v92
	v_pk_mul_f32 v[96:97], v[96:97], v[244:245] op_sel_hi:[1,0]
	v_mov_b32_e32 v92, v89
	v_mul_f32_e32 v88, 0xbfb8aa3b, v97
	v_exp_f32_e32 v88, v88
	s_nop 0
	v_add_f32_e32 v88, 1.0, v88
	v_rcp_f32_e32 v88, v88
	s_nop 0
	v_mul_f32_e32 v88, v97, v88
	v_mul_f32_e32 v96, v96, v88
	v_pk_mul_f32 v[88:89], v[92:93], v[244:245] op_sel_hi:[1,0]
	s_nop 0
	v_mul_f32_e32 v92, 0xbfb8aa3b, v89
	v_exp_f32_e32 v92, v92
	s_nop 0
	v_add_f32_e32 v92, 1.0, v92
	v_rcp_f32_e32 v92, v92
	s_nop 0
	v_mul_f32_e32 v89, v89, v92
	v_mul_f32_e32 v92, v88, v89
	v_mov_b32_e32 v88, v90
	v_mov_b32_e32 v89, v94
	v_pk_mul_f32 v[88:89], v[88:89], v[244:245] op_sel_hi:[1,0]
	v_mov_b32_e32 v94, v91
	v_mul_f32_e32 v90, 0xbfb8aa3b, v89
	v_exp_f32_e32 v90, v90
	s_nop 0
	v_add_f32_e32 v90, 1.0, v90
	v_rcp_f32_e32 v90, v90
	s_nop 0
	v_mul_f32_e32 v89, v89, v90
	v_mul_f32_e32 v90, v88, v89
	v_pk_mul_f32 v[88:89], v[94:95], v[244:245] op_sel_hi:[1,0]
	s_nop 0
	v_mul_f32_e32 v91, 0xbfb8aa3b, v89
	v_exp_f32_e32 v91, v91
	s_nop 0
	v_add_f32_e32 v91, 1.0, v91
	v_rcp_f32_e32 v91, v91
	s_nop 0
	v_mul_f32_e32 v89, v89, v91
	v_mul_f32_e32 v91, v88, v89
	v_mov_b32_e32 v88, v80
	v_mov_b32_e32 v89, v84
	v_pk_mul_f32 v[88:89], v[88:89], v[244:245] op_sel_hi:[1,0]
	v_mov_b32_e32 v84, v81
	v_mul_f32_e32 v80, 0xbfb8aa3b, v89
	v_exp_f32_e32 v80, v80
	s_nop 0
	v_add_f32_e32 v80, 1.0, v80
	v_rcp_f32_e32 v80, v80
	s_nop 0
	v_mul_f32_e32 v80, v89, v80
	v_mul_f32_e32 v88, v88, v80
	v_pk_mul_f32 v[80:81], v[84:85], v[244:245] op_sel_hi:[1,0]
	s_nop 0
	v_mul_f32_e32 v84, 0xbfb8aa3b, v81
	v_exp_f32_e32 v84, v84
	s_nop 0
	v_add_f32_e32 v84, 1.0, v84
	v_rcp_f32_e32 v84, v84
	s_nop 0
	v_mul_f32_e32 v81, v81, v84
	v_mul_f32_e32 v84, v80, v81
	v_mov_b32_e32 v80, v82
	v_mov_b32_e32 v81, v86
	v_pk_mul_f32 v[80:81], v[80:81], v[244:245] op_sel_hi:[1,0]
	v_mov_b32_e32 v86, v83
	v_mul_f32_e32 v82, 0xbfb8aa3b, v81
	v_exp_f32_e32 v82, v82
	s_nop 0
	v_add_f32_e32 v82, 1.0, v82
	v_rcp_f32_e32 v82, v82
	s_nop 0
	v_mul_f32_e32 v81, v81, v82
	v_mul_f32_e32 v85, v80, v81
	v_pk_mul_f32 v[80:81], v[86:87], v[244:245] op_sel_hi:[1,0]
	s_nop 0
	v_mul_f32_e32 v82, 0xbfb8aa3b, v81
	v_exp_f32_e32 v82, v82
	s_nop 0
	v_add_f32_e32 v82, 1.0, v82
	v_rcp_f32_e32 v82, v82
	s_nop 0
	v_mul_f32_e32 v81, v81, v82
	v_mul_f32_e32 v83, v80, v81
	v_cvt_pk_bf16_f32 v80, v96, v92
	v_cvt_pk_bf16_f32 v81, v90, v91
	v_cvt_pk_bf16_f32 v82, v88, v84
	v_cvt_pk_bf16_f32 v83, v85, v83
	v_mad_i64_i32 v[84:85], s[16:17], v158, s3, v[112:113]
	v_lshl_add_u64 v[84:85], v[84:85], 0, v[114:115]
	global_store_dwordx4 v[84:85], v[80:83], off
	s_nop 1
	v_mov_b32_e32 v80, v72
	v_mov_b32_e32 v81, v76
	v_pk_mul_f32 v[80:81], v[80:81], v[186:187] op_sel_hi:[1,0]
	v_mov_b32_e32 v76, v73
	v_mul_f32_e32 v72, 0xbfb8aa3b, v81
	v_exp_f32_e32 v72, v72
	s_nop 0
	v_add_f32_e32 v72, 1.0, v72
	v_rcp_f32_e32 v72, v72
	s_nop 0
	v_mul_f32_e32 v72, v81, v72
	v_mul_f32_e32 v80, v80, v72
	v_pk_mul_f32 v[72:73], v[76:77], v[186:187] op_sel_hi:[1,0]
	s_nop 0
	v_mul_f32_e32 v76, 0xbfb8aa3b, v73
	v_exp_f32_e32 v76, v76
	s_nop 0
	v_add_f32_e32 v76, 1.0, v76
	v_rcp_f32_e32 v76, v76
	s_nop 0
	v_mul_f32_e32 v73, v73, v76
	v_mul_f32_e32 v76, v72, v73
	v_mov_b32_e32 v72, v74
	v_mov_b32_e32 v73, v78
	v_pk_mul_f32 v[72:73], v[72:73], v[186:187] op_sel_hi:[1,0]
	v_mov_b32_e32 v78, v75
	v_mul_f32_e32 v74, 0xbfb8aa3b, v73
	v_exp_f32_e32 v74, v74
	s_nop 0
	v_add_f32_e32 v74, 1.0, v74
	v_rcp_f32_e32 v74, v74
	s_nop 0
	v_mul_f32_e32 v73, v73, v74
	v_mul_f32_e32 v74, v72, v73
	v_pk_mul_f32 v[72:73], v[78:79], v[186:187] op_sel_hi:[1,0]
	s_nop 0
	v_mul_f32_e32 v75, 0xbfb8aa3b, v73
	v_exp_f32_e32 v75, v75
	s_nop 0
	v_add_f32_e32 v75, 1.0, v75
	v_rcp_f32_e32 v75, v75
	s_nop 0
	v_mul_f32_e32 v73, v73, v75
	v_mul_f32_e32 v75, v72, v73
	v_mov_b32_e32 v72, v64
	v_mov_b32_e32 v73, v68
	v_pk_mul_f32 v[72:73], v[72:73], v[186:187] op_sel_hi:[1,0]
	v_mov_b32_e32 v68, v65
	v_mul_f32_e32 v64, 0xbfb8aa3b, v73
	v_exp_f32_e32 v64, v64
	s_nop 0
	v_add_f32_e32 v64, 1.0, v64
	v_rcp_f32_e32 v64, v64
	s_nop 0
	v_mul_f32_e32 v64, v73, v64
	v_mul_f32_e32 v72, v72, v64
	v_pk_mul_f32 v[64:65], v[68:69], v[186:187] op_sel_hi:[1,0]
	s_nop 0
	v_mul_f32_e32 v68, 0xbfb8aa3b, v65
	v_exp_f32_e32 v68, v68
	s_nop 0
	v_add_f32_e32 v68, 1.0, v68
	v_rcp_f32_e32 v68, v68
	s_nop 0
	v_mul_f32_e32 v65, v65, v68
	v_mul_f32_e32 v68, v64, v65
	v_mov_b32_e32 v64, v66
	v_mov_b32_e32 v65, v70
	v_pk_mul_f32 v[64:65], v[64:65], v[186:187] op_sel_hi:[1,0]
	v_mov_b32_e32 v70, v67
	v_mul_f32_e32 v66, 0xbfb8aa3b, v65
	v_exp_f32_e32 v66, v66
	s_nop 0
	v_add_f32_e32 v66, 1.0, v66
	v_rcp_f32_e32 v66, v66
	s_nop 0
	v_mul_f32_e32 v65, v65, v66
	v_mul_f32_e32 v69, v64, v65
	v_pk_mul_f32 v[64:65], v[70:71], v[186:187] op_sel_hi:[1,0]
	s_nop 0
	v_mul_f32_e32 v66, 0xbfb8aa3b, v65
	v_exp_f32_e32 v66, v66
	s_nop 0
	v_add_f32_e32 v66, 1.0, v66
; __device__ __forceinline__ unsigned cvt_pk_bf16(float lo, float hi) { unsigned r; asm volatile("v_cvt_pk_bf16_f32 %0, %1, %2" : "=v"(r) : "v"(lo), "v"(hi)); return r; }
; __device__ __forceinline__ float sigmoidf_(float x) { return __builtin_amdgcn_rcpf(1.0f + __expf(-x)); }
;     __device__ __forceinline__ void operator()(const f32x4 (&acc)[2][2][4][2], const Unit& u, int wr, int wc, int fr, int fq) const {
;     ...
;         for (int ai = 0; ai < 2; ++ai)
; #pragma unroll
;             for (int m = 0; m < 4; ++m) {
;                 const int row = row0 + ai * 128 + m * 16; const float s = sv[ai][m];
;                 float o[8];
; #pragma unroll
;                 for (int n = 0; n < 2; ++n)
; #pragma unroll
;                     for (int j = 0; j < 4; ++j) { const float g = acc[ai][0][m][n][j] * s, up = acc[ai][1][m][n][j] * s; o[n * 4 + j] = g * sigmoidf_(g) * up; }
;                 u32x4 w; w.x = cvt_pk_bf16(o[0], o[1]); w.y = cvt_pk_bf16(o[2], o[3]); w.z = cvt_pk_bf16(o[4], o[5]); w.w = cvt_pk_bf16(o[6], o[7]);
;                 *(u32x4*)(ACT + (size_t)row * FF + col0) = w;
	v_rcp_f32_e32 v66, v66
	s_nop 0
	v_mul_f32_e32 v65, v65, v66
	v_mul_f32_e32 v67, v64, v65
	v_cvt_pk_bf16_f32 v64, v80, v76
	v_cvt_pk_bf16_f32 v65, v74, v75
	v_cvt_pk_bf16_f32 v66, v72, v68
	v_cvt_pk_bf16_f32 v67, v69, v67
	v_mad_i64_i32 v[68:69], s[16:17], v154, s3, v[112:113]
	v_lshl_add_u64 v[68:69], v[68:69], 0, v[114:115]
	global_store_dwordx4 v[68:69], v[64:67], off
	s_nop 1
	v_mov_b32_e32 v64, v56
	v_mov_b32_e32 v65, v60
	v_pk_mul_f32 v[64:65], v[64:65], v[152:153] op_sel_hi:[1,0]
	v_mov_b32_e32 v60, v57
	v_mul_f32_e32 v56, 0xbfb8aa3b, v65
	v_exp_f32_e32 v56, v56
	s_nop 0
	v_add_f32_e32 v56, 1.0, v56
	v_rcp_f32_e32 v56, v56
	s_nop 0
	v_mul_f32_e32 v56, v65, v56
	v_mul_f32_e32 v64, v64, v56
	v_pk_mul_f32 v[56:57], v[60:61], v[152:153] op_sel_hi:[1,0]
	s_nop 0
	v_mul_f32_e32 v60, 0xbfb8aa3b, v57
	v_exp_f32_e32 v60, v60
	s_nop 0
	v_add_f32_e32 v60, 1.0, v60
	v_rcp_f32_e32 v60, v60
	s_nop 0
	v_mul_f32_e32 v57, v57, v60
	v_mul_f32_e32 v60, v56, v57
	v_mov_b32_e32 v56, v58
	v_mov_b32_e32 v57, v62
	v_pk_mul_f32 v[56:57], v[56:57], v[152:153] op_sel_hi:[1,0]
	v_mov_b32_e32 v62, v59
	v_mul_f32_e32 v58, 0xbfb8aa3b, v57
	v_exp_f32_e32 v58, v58
	s_nop 0
	v_add_f32_e32 v58, 1.0, v58
	v_rcp_f32_e32 v58, v58
	s_nop 0
	v_mul_f32_e32 v57, v57, v58
	v_mul_f32_e32 v58, v56, v57
	v_pk_mul_f32 v[56:57], v[62:63], v[152:153] op_sel_hi:[1,0]
	s_nop 0
	v_mul_f32_e32 v59, 0xbfb8aa3b, v57
	v_exp_f32_e32 v59, v59
	s_nop 0
	v_add_f32_e32 v59, 1.0, v59
	v_rcp_f32_e32 v59, v59
	s_nop 0
	v_mul_f32_e32 v57, v57, v59
	v_mul_f32_e32 v59, v56, v57
	v_mov_b32_e32 v56, v48
	v_mov_b32_e32 v57, v52
	v_pk_mul_f32 v[56:57], v[56:57], v[152:153] op_sel_hi:[1,0]
	v_mov_b32_e32 v52, v49
	v_mul_f32_e32 v48, 0xbfb8aa3b, v57
	v_exp_f32_e32 v48, v48
	s_nop 0
	v_add_f32_e32 v48, 1.0, v48
	v_rcp_f32_e32 v48, v48
	s_nop 0
	v_mul_f32_e32 v48, v57, v48
	v_mul_f32_e32 v56, v56, v48
	v_pk_mul_f32 v[48:49], v[52:53], v[152:153] op_sel_hi:[1,0]
	s_nop 0
	v_mul_f32_e32 v52, 0xbfb8aa3b, v49
	v_exp_f32_e32 v52, v52
	s_nop 0
	v_add_f32_e32 v52, 1.0, v52
	v_rcp_f32_e32 v52, v52
	s_nop 0
	v_mul_f32_e32 v49, v49, v52
	v_mul_f32_e32 v52, v48, v49
	v_mov_b32_e32 v48, v50
	v_mov_b32_e32 v49, v54
	v_pk_mul_f32 v[48:49], v[48:49], v[152:153] op_sel_hi:[1,0]
	v_mov_b32_e32 v54, v51
	v_mul_f32_e32 v50, 0xbfb8aa3b, v49
	v_exp_f32_e32 v50, v50
	s_nop 0
	v_add_f32_e32 v50, 1.0, v50
	v_rcp_f32_e32 v50, v50
	s_nop 0
	v_mul_f32_e32 v49, v49, v50
	v_mul_f32_e32 v53, v48, v49
	v_pk_mul_f32 v[48:49], v[54:55], v[152:153] op_sel_hi:[1,0]
	s_nop 0
	v_mul_f32_e32 v50, 0xbfb8aa3b, v49
	v_exp_f32_e32 v50, v50
	s_nop 0
	v_add_f32_e32 v50, 1.0, v50
	v_rcp_f32_e32 v50, v50
	s_nop 0
	v_mul_f32_e32 v49, v49, v50
	v_mul_f32_e32 v51, v48, v49
	v_cvt_pk_bf16_f32 v48, v64, v60
	v_cvt_pk_bf16_f32 v49, v58, v59
	v_cvt_pk_bf16_f32 v50, v56, v52
	v_cvt_pk_bf16_f32 v51, v53, v51
	v_mad_i64_i32 v[52:53], s[16:17], v161, s3, v[112:113]
	v_lshl_add_u64 v[52:53], v[52:53], 0, v[114:115]
	global_store_dwordx4 v[52:53], v[48:51], off
	s_nop 1
	v_mov_b32_e32 v48, v40
	v_mov_b32_e32 v49, v44
	v_pk_mul_f32 v[48:49], v[48:49], v[150:151] op_sel_hi:[1,0]
	v_mov_b32_e32 v44, v41
	v_mul_f32_e32 v40, 0xbfb8aa3b, v49
	v_exp_f32_e32 v40, v40
	s_nop 0
	v_add_f32_e32 v40, 1.0, v40
	v_rcp_f32_e32 v40, v40
	s_nop 0
	v_mul_f32_e32 v40, v49, v40
	v_mul_f32_e32 v48, v48, v40
	v_pk_mul_f32 v[40:41], v[44:45], v[150:151] op_sel_hi:[1,0]
	s_nop 0
	v_mul_f32_e32 v44, 0xbfb8aa3b, v41
	v_exp_f32_e32 v44, v44
	s_nop 0
	v_add_f32_e32 v44, 1.0, v44
	v_rcp_f32_e32 v44, v44
	s_nop 0
	v_mul_f32_e32 v41, v41, v44
	v_mul_f32_e32 v44, v40, v41
	v_mov_b32_e32 v40, v42
	v_mov_b32_e32 v41, v46
	v_pk_mul_f32 v[40:41], v[40:41], v[150:151] op_sel_hi:[1,0]
	v_mov_b32_e32 v46, v43
	v_mul_f32_e32 v42, 0xbfb8aa3b, v41
	v_exp_f32_e32 v42, v42
	s_nop 0
	v_add_f32_e32 v42, 1.0, v42
	v_rcp_f32_e32 v42, v42
	s_nop 0
	v_mul_f32_e32 v41, v41, v42
	v_mul_f32_e32 v42, v40, v41
	v_pk_mul_f32 v[40:41], v[46:47], v[150:151] op_sel_hi:[1,0]
	s_nop 0
	v_mul_f32_e32 v43, 0xbfb8aa3b, v41
	v_exp_f32_e32 v43, v43
	s_nop 0
	v_add_f32_e32 v43, 1.0, v43
	v_rcp_f32_e32 v43, v43
	s_nop 0
	v_mul_f32_e32 v41, v41, v43
	v_mul_f32_e32 v43, v40, v41
	v_mov_b32_e32 v40, v32
	v_mov_b32_e32 v41, v36
	v_pk_mul_f32 v[40:41], v[40:41], v[150:151] op_sel_hi:[1,0]
	v_mov_b32_e32 v36, v33
	v_mul_f32_e32 v32, 0xbfb8aa3b, v41
	v_exp_f32_e32 v32, v32
	s_nop 0
	v_add_f32_e32 v32, 1.0, v32
	v_rcp_f32_e32 v32, v32
	s_nop 0
	v_mul_f32_e32 v32, v41, v32
	v_mul_f32_e32 v40, v40, v32
	v_pk_mul_f32 v[32:33], v[36:37], v[150:151] op_sel_hi:[1,0]
	s_nop 0
	v_mul_f32_e32 v36, 0xbfb8aa3b, v33
	v_exp_f32_e32 v36, v36
	s_nop 0
	v_add_f32_e32 v36, 1.0, v36
	v_rcp_f32_e32 v36, v36
	s_nop 0
	v_mul_f32_e32 v33, v33, v36
	v_mul_f32_e32 v36, v32, v33
	v_mov_b32_e32 v32, v34
	v_mov_b32_e32 v33, v38
	v_pk_mul_f32 v[32:33], v[32:33], v[150:151] op_sel_hi:[1,0]
	v_mov_b32_e32 v38, v35
	v_mul_f32_e32 v34, 0xbfb8aa3b, v33
	v_exp_f32_e32 v34, v34
	s_nop 0
	v_add_f32_e32 v34, 1.0, v34
	v_rcp_f32_e32 v34, v34
	s_nop 0
	v_mul_f32_e32 v33, v33, v34
	v_mul_f32_e32 v37, v32, v33
	v_pk_mul_f32 v[32:33], v[38:39], v[150:151] op_sel_hi:[1,0]
	s_nop 0
	v_mul_f32_e32 v34, 0xbfb8aa3b, v33
	v_exp_f32_e32 v34, v34
	s_nop 0
	v_add_f32_e32 v34, 1.0, v34
	v_rcp_f32_e32 v34, v34
	s_nop 0
	v_mul_f32_e32 v33, v33, v34
	v_mul_f32_e32 v35, v32, v33
	v_cvt_pk_bf16_f32 v32, v48, v44
	v_cvt_pk_bf16_f32 v33, v42, v43
	v_cvt_pk_bf16_f32 v34, v40, v36
	v_cvt_pk_bf16_f32 v35, v37, v35
	v_mad_i64_i32 v[36:37], s[16:17], v159, s3, v[112:113]
; __device__ __forceinline__ unsigned cvt_pk_bf16(float lo, float hi) { unsigned r; asm volatile("v_cvt_pk_bf16_f32 %0, %1, %2" : "=v"(r) : "v"(lo), "v"(hi)); return r; }
; #define PG8_BAR __builtin_amdgcn_s_barrier()
; __device__ __forceinline__ float sigmoidf_(float x) { return __builtin_amdgcn_rcpf(1.0f + __expf(-x)); }
; template <class Epi, class Sched, bool ALIGN_EPI = false, bool SP2 = false>
; __device__ __forceinline__ void gemm_phase(PG8_LAS unsigned char* lds, const Gemm g, const Sched& S, const Epi& E) {
;     ...
;         if constexpr (!Epi::AFTER_DRAIN) { E(acc, cur, wr, wc, fr, fq); S.done(cur); }
;         if (!has_next) break;
; #pragma unroll
;         for (int a = 0; a < 2; ++a)
; #pragma unroll
;             for (int b = 0; b < 2; ++b)
; #pragma unroll
;                 for (int m = 0; m < 4; ++m)
; #pragma unroll
;                     for (int n = 0; n < 2; ++n) acc[a][b][m][n] = (f32x4){0.f, 0.f, 0.f, 0.f};
;         cur = nxt; cA = nA; cB = nB; ++ui;
;         if constexpr (ALIGN_EPI) { if (wr == 1) PG8_BAR; }
;     __device__ __forceinline__ void operator()(const f32x4 (&acc)[2][2][4][2], const Unit& u, int wr, int wc, int fr, int fq) const {
;     ...
;         for (int ai = 0; ai < 2; ++ai)
; #pragma unroll
;             for (int m = 0; m < 4; ++m) {
;                 const int row = row0 + ai * 128 + m * 16; const float s = sv[ai][m];
;                 float o[8];
; #pragma unroll
;                 for (int n = 0; n < 2; ++n)
; #pragma unroll
;                     for (int j = 0; j < 4; ++j) { const float g = acc[ai][0][m][n][j] * s, up = acc[ai][1][m][n][j] * s; o[n * 4 + j] = g * sigmoidf_(g) * up; }
;                 u32x4 w; w.x = cvt_pk_bf16(o[0], o[1]); w.y = cvt_pk_bf16(o[2], o[3]); w.z = cvt_pk_bf16(o[4], o[5]); w.w = cvt_pk_bf16(o[6], o[7]);
;                 *(u32x4*)(ACT + (size_t)row * FF + col0) = w;
	v_lshl_add_u64 v[36:37], v[36:37], 0, v[114:115]
	global_store_dwordx4 v[36:37], v[32:35], off
	s_nop 1
	v_mov_b32_e32 v32, v24
	v_mov_b32_e32 v33, v28
	v_pk_mul_f32 v[32:33], v[32:33], v[148:149] op_sel_hi:[1,0]
	v_mov_b32_e32 v28, v25
	v_mul_f32_e32 v24, 0xbfb8aa3b, v33
	v_exp_f32_e32 v24, v24
	s_nop 0
	v_add_f32_e32 v24, 1.0, v24
	v_rcp_f32_e32 v24, v24
	s_nop 0
	v_mul_f32_e32 v24, v33, v24
	v_mul_f32_e32 v32, v32, v24
	v_pk_mul_f32 v[24:25], v[28:29], v[148:149] op_sel_hi:[1,0]
	s_nop 0
	v_mul_f32_e32 v28, 0xbfb8aa3b, v25
	v_exp_f32_e32 v28, v28
	s_nop 0
	v_add_f32_e32 v28, 1.0, v28
	v_rcp_f32_e32 v28, v28
	s_nop 0
	v_mul_f32_e32 v25, v25, v28
	v_mul_f32_e32 v28, v24, v25
	v_mov_b32_e32 v24, v26
	v_mov_b32_e32 v25, v30
	v_pk_mul_f32 v[24:25], v[24:25], v[148:149] op_sel_hi:[1,0]
	v_mov_b32_e32 v30, v27
	v_mul_f32_e32 v26, 0xbfb8aa3b, v25
	v_exp_f32_e32 v26, v26
	s_nop 0
	v_add_f32_e32 v26, 1.0, v26
	v_rcp_f32_e32 v26, v26
	s_nop 0
	v_mul_f32_e32 v25, v25, v26
	v_mul_f32_e32 v26, v24, v25
	v_pk_mul_f32 v[24:25], v[30:31], v[148:149] op_sel_hi:[1,0]
	s_nop 0
	v_mul_f32_e32 v27, 0xbfb8aa3b, v25
	v_exp_f32_e32 v27, v27
	s_nop 0
	v_add_f32_e32 v27, 1.0, v27
	v_rcp_f32_e32 v27, v27
	s_nop 0
	v_mul_f32_e32 v25, v25, v27
	v_mul_f32_e32 v27, v24, v25
	v_mov_b32_e32 v24, v16
	v_mov_b32_e32 v25, v20
	v_pk_mul_f32 v[24:25], v[24:25], v[148:149] op_sel_hi:[1,0]
	v_mov_b32_e32 v20, v17
	v_mul_f32_e32 v16, 0xbfb8aa3b, v25
	v_exp_f32_e32 v16, v16
	s_nop 0
	v_add_f32_e32 v16, 1.0, v16
	v_rcp_f32_e32 v16, v16
	s_nop 0
	v_mul_f32_e32 v16, v25, v16
	v_mul_f32_e32 v24, v24, v16
	v_pk_mul_f32 v[16:17], v[20:21], v[148:149] op_sel_hi:[1,0]
	s_nop 0
	v_mul_f32_e32 v20, 0xbfb8aa3b, v17
	v_exp_f32_e32 v20, v20
	s_nop 0
	v_add_f32_e32 v20, 1.0, v20
	v_rcp_f32_e32 v20, v20
	s_nop 0
	v_mul_f32_e32 v17, v17, v20
	v_mul_f32_e32 v20, v16, v17
	v_mov_b32_e32 v16, v18
	v_mov_b32_e32 v17, v22
	v_pk_mul_f32 v[16:17], v[16:17], v[148:149] op_sel_hi:[1,0]
	v_mov_b32_e32 v22, v19
	v_mul_f32_e32 v18, 0xbfb8aa3b, v17
	v_exp_f32_e32 v18, v18
	s_nop 0
	v_add_f32_e32 v18, 1.0, v18
	v_rcp_f32_e32 v18, v18
	s_nop 0
	v_mul_f32_e32 v17, v17, v18
	v_mul_f32_e32 v21, v16, v17
	v_pk_mul_f32 v[16:17], v[22:23], v[148:149] op_sel_hi:[1,0]
	s_nop 0
	v_mul_f32_e32 v18, 0xbfb8aa3b, v17
	v_exp_f32_e32 v18, v18
	s_nop 0
	v_add_f32_e32 v18, 1.0, v18
	v_rcp_f32_e32 v18, v18
	s_nop 0
	v_mul_f32_e32 v17, v17, v18
	v_mul_f32_e32 v19, v16, v17
	v_cvt_pk_bf16_f32 v16, v32, v28
	v_cvt_pk_bf16_f32 v17, v26, v27
	v_cvt_pk_bf16_f32 v18, v24, v20
	v_cvt_pk_bf16_f32 v19, v21, v19
	v_mad_i64_i32 v[20:21], s[16:17], v157, s3, v[112:113]
	v_lshl_add_u64 v[20:21], v[20:21], 0, v[114:115]
	global_store_dwordx4 v[20:21], v[16:19], off
	s_nop 1
	v_mov_b32_e32 v16, v8
	v_mov_b32_e32 v17, v12
	v_pk_mul_f32 v[16:17], v[16:17], v[188:189] op_sel_hi:[1,0]
	v_mov_b32_e32 v12, v9
	v_mul_f32_e32 v8, 0xbfb8aa3b, v17
	v_exp_f32_e32 v8, v8
	s_nop 0
	v_add_f32_e32 v8, 1.0, v8
	v_rcp_f32_e32 v8, v8
	s_nop 0
	v_mul_f32_e32 v8, v17, v8
	v_mul_f32_e32 v16, v16, v8
	v_pk_mul_f32 v[8:9], v[12:13], v[188:189] op_sel_hi:[1,0]
	s_nop 0
	v_mul_f32_e32 v12, 0xbfb8aa3b, v9
	v_exp_f32_e32 v12, v12
	s_nop 0
	v_add_f32_e32 v12, 1.0, v12
	v_rcp_f32_e32 v12, v12
	s_nop 0
	v_mul_f32_e32 v9, v9, v12
	v_mul_f32_e32 v12, v8, v9
	v_mov_b32_e32 v8, v10
	v_mov_b32_e32 v9, v14
	v_pk_mul_f32 v[8:9], v[8:9], v[188:189] op_sel_hi:[1,0]
	v_mov_b32_e32 v14, v11
	v_mul_f32_e32 v10, 0xbfb8aa3b, v9
	v_exp_f32_e32 v10, v10
	s_nop 0
	v_add_f32_e32 v10, 1.0, v10
	v_rcp_f32_e32 v10, v10
	s_nop 0
	v_mul_f32_e32 v9, v9, v10
	v_mul_f32_e32 v10, v8, v9
	v_pk_mul_f32 v[8:9], v[14:15], v[188:189] op_sel_hi:[1,0]
	s_nop 0
	v_mul_f32_e32 v11, 0xbfb8aa3b, v9
	v_exp_f32_e32 v11, v11
	s_nop 0
	v_add_f32_e32 v11, 1.0, v11
	v_rcp_f32_e32 v11, v11
	s_nop 0
	v_mul_f32_e32 v9, v9, v11
	v_mul_f32_e32 v11, v8, v9
	v_mov_b32_e32 v8, v0
	v_mov_b32_e32 v9, v4
	v_pk_mul_f32 v[8:9], v[8:9], v[188:189] op_sel_hi:[1,0]
	v_mov_b32_e32 v4, v1
	v_mul_f32_e32 v0, 0xbfb8aa3b, v9
	v_exp_f32_e32 v0, v0
	s_nop 0
	v_add_f32_e32 v0, 1.0, v0
	v_rcp_f32_e32 v0, v0
	s_nop 0
	v_mul_f32_e32 v0, v9, v0
	v_mul_f32_e32 v8, v8, v0
	v_pk_mul_f32 v[0:1], v[4:5], v[188:189] op_sel_hi:[1,0]
	s_nop 0
	v_mul_f32_e32 v4, 0xbfb8aa3b, v1
	v_exp_f32_e32 v4, v4
	s_nop 0
	v_add_f32_e32 v4, 1.0, v4
	v_rcp_f32_e32 v4, v4
	s_nop 0
	v_mul_f32_e32 v1, v1, v4
	v_mul_f32_e32 v4, v0, v1
	v_mov_b32_e32 v0, v2
	v_mov_b32_e32 v1, v6
	v_pk_mul_f32 v[0:1], v[0:1], v[188:189] op_sel_hi:[1,0]
	v_mov_b32_e32 v6, v3
	v_mul_f32_e32 v2, 0xbfb8aa3b, v1
	v_exp_f32_e32 v2, v2
	s_nop 0
	v_add_f32_e32 v2, 1.0, v2
	v_rcp_f32_e32 v2, v2
	s_nop 0
	v_mul_f32_e32 v1, v1, v2
	v_mul_f32_e32 v5, v0, v1
	v_pk_mul_f32 v[0:1], v[6:7], v[188:189] op_sel_hi:[1,0]
	s_nop 0
	v_mul_f32_e32 v2, 0xbfb8aa3b, v1
	v_exp_f32_e32 v2, v2
	s_nop 0
	v_add_f32_e32 v2, 1.0, v2
	v_rcp_f32_e32 v2, v2
	s_nop 0
	v_mul_f32_e32 v1, v1, v2
	v_mul_f32_e32 v3, v0, v1
	v_cvt_pk_bf16_f32 v0, v16, v12
	v_cvt_pk_bf16_f32 v1, v10, v11
	v_cvt_pk_bf16_f32 v2, v8, v4
	v_cvt_pk_bf16_f32 v3, v5, v3
	v_mad_i64_i32 v[4:5], s[16:17], v155, s3, v[112:113]
	v_lshl_add_u64 v[4:5], v[4:5], 0, v[114:115]
	s_mov_b64 s[16:17], -1
	global_store_dwordx4 v[4:5], v[0:3], off
	s_cbranch_vccnz .LBB0_721
	s_andn2_b64 vcc, exec, s[0:1]
	s_cbranch_vccnz .LBB0_720
	s_barrier
	s_branch .LBB0_720
.LBB0_731:
	s_waitcnt vmcnt(0)
	v_mov_b32_e32 v186, 0x600
	v_mov_b32_e32 v188, 0x3c0881c4
	v_readlane_b32 s0, v254, 18
	s_mov_b32 s4, s0
	v_readlane_b32 s22, v254, 19
	s_barrier
